# as v41 but the dequeue result is consumed without a second wait (the unit's first vmcnt(0) already covers the atomic, the oldest VMEM op of the unit)
# baseline (speedup 1.0000x reference)
.LBB0_542:
	v_mov_b32_e32 v0, s64
	ds_write_b32 v0, v239
	s_branch .LBB0_422
